# split (arrive / lazy-wait) barrier on the gate-up -> down seam, write-through SwiGLU and generic epilogue stores
# baseline (speedup 1.0000x reference)
.LBB0_122:
	v_readlane_b32 s12, v244, 8
	s_cmp_eq_u32 s12, 0
	s_cbranch_scc1 .Llz_done
	v_cmp_eq_u32_e32 vcc, 0, v147
	s_and_saveexec_b64 s[14:15], vcc
	s_cbranch_execz .Llz_join
	v_readlane_b32 s12, v241, 26
	v_readlane_b32 s13, v241, 27
	v_readlane_b32 vcc_lo, v244, 9
	s_sub_u32 s12, s12, 0x1000
	s_subb_u32 s13, s13, 0
	s_nop 4
.Llz_poll:
	global_load_dword v248, v137, s[12:13] sc1
	global_load_dword v249, v137, s[12:13] offset:256 sc1
	global_load_dword v250, v137, s[12:13] offset:512 sc1
	global_load_dword v251, v137, s[12:13] offset:768 sc1
	global_load_dword v252, v137, s[12:13] offset:1024 sc1
	global_load_dword v253, v137, s[12:13] offset:1280 sc1
	global_load_dword v254, v137, s[12:13] offset:1536 sc1
	global_load_dword v255, v137, s[12:13] offset:1792 sc1
	s_waitcnt vmcnt(0)
	v_add_u32_e32 v248, v248, v249
	v_add3_u32 v248, v248, v250, v251
	v_add3_u32 v248, v248, v252, v253
	v_add3_u32 v248, v248, v254, v255
	s_nop 0
	v_readfirstlane_b32 vcc_hi, v248
	s_cmp_ge_u32 vcc_hi, vcc_lo
	s_cbranch_scc1 .Llz_ok
	s_sleep 1
	s_branch .Llz_poll

.Llz_join:
	s_mov_b64 exec, s[14:15]
	s_barrier
	s_mov_b32 s12, 0
	v_writelane_b32 v244, s12, 8

.LBB0_162:
	s_cmp_gt_i32 s41, 4
	s_cbranch_scc0 .LBB0_167
	s_cmp_eq_u32 s41, 5
	s_mov_b64 s[94:95], -1
	s_cbranch_scc0 .LBB0_166
	s_add_i32 s7, s47, -4
	s_cmp_gt_u32 s7, 7
	s_cselect_b64 s[94:95], -1, 0
	s_cmp_lt_u32 s7, 8
	s_cbranch_scc0 .LBB0_166
	v_mov_b64_e32 v[128:129], s[28:29]
	s_movk_i32 s19, 0x1400
	v_mad_i64_i32 v[130:131], s[82:83], v152, s19, v[128:129]
	s_lshl_b32 s34, s47, 8
	v_lshl_add_u64 v[130:131], v[130:131], 0, s[34:35]
	v_lshlrev_b32_e32 v136, 1, v146
	v_lshl_add_u64 v[134:135], v[130:131], 0, v[136:137]
	s_waitcnt vmcnt(0)
	v_fmamk_f32 v130, v167, 0x3a800000, v162
	v_cmp_gt_f32_e32 vcc, s40, v130
	v_mul_f32_e32 v131, 0x4b800000, v130
	v_pk_mul_f32 v[132:133], v[126:127], v[118:119]
	v_cndmask_b32_e32 v130, v130, v131, vcc
	v_rsq_f32_e32 v130, v130
	v_pk_mul_f32 v[154:155], v[124:125], v[116:117]
	v_pk_mul_f32 v[156:157], v[122:123], v[114:115]
	v_pk_mul_f32 v[158:159], v[120:121], v[112:113]
	v_mul_f32_e32 v131, 0x45800000, v130
	v_cndmask_b32_e32 v130, v130, v131, vcc
	v_cndmask_b32_e64 v130, v130, 1.0, s[14:15]
	v_mul_f32_e32 v130, v130, v130
	s_lshl_b32 s7, s47, 7
	v_pk_mul_f32 v[132:133], v[132:133], v[130:131] op_sel_hi:[1,0]
	v_pk_mul_f32 v[154:155], v[154:155], v[130:131] op_sel_hi:[1,0]
	v_pk_mul_f32 v[156:157], v[156:157], v[130:131] op_sel_hi:[1,0]
	v_pk_mul_f32 v[158:159], v[158:159], v[130:131] op_sel_hi:[1,0]
	v_cvt_pk_bf16_f32 v130, v154, v155
	v_cvt_pk_bf16_f32 v131, v132, v133
	v_cvt_pk_bf16_f32 v133, v156, v157
	s_add_i32 s34, s7, 0xfffffe00
	v_cvt_pk_bf16_f32 v132, v158, v159
	global_store_dwordx4 v[134:135], v[130:133], off offset:1024 sc1
	s_lshl_b64 s[96:97], s[34:35], 1
	v_pk_mul_f32 v[154:155], v[108:109], v[100:101]
	v_or_b32_e32 v130, 16, v152
	v_mad_i64_i32 v[130:131], s[82:83], v130, s19, v[128:129]
	v_lshl_add_u64 v[130:131], v[130:131], 0, s[96:97]
	v_lshl_add_u64 v[134:135], v[130:131], 0, v[136:137]
	v_fmamk_f32 v130, v168, 0x3a800000, v162
	v_cmp_gt_f32_e32 vcc, s40, v130
	v_mul_f32_e32 v131, 0x4b800000, v130
	v_pk_mul_f32 v[132:133], v[110:111], v[102:103]
	v_cndmask_b32_e32 v130, v130, v131, vcc
	v_rsq_f32_e32 v130, v130
	v_pk_mul_f32 v[156:157], v[106:107], v[98:99]
	v_pk_mul_f32 v[158:159], v[104:105], v[96:97]
	v_mul_f32_e32 v131, 0x45800000, v130
	v_cndmask_b32_e32 v130, v130, v131, vcc
	v_cndmask_b32_e64 v130, v130, 1.0, s[14:15]
	v_mul_f32_e32 v130, v130, v130
	v_pk_mul_f32 v[132:133], v[132:133], v[130:131] op_sel_hi:[1,0]
	v_pk_mul_f32 v[154:155], v[154:155], v[130:131] op_sel_hi:[1,0]
	v_pk_mul_f32 v[156:157], v[156:157], v[130:131] op_sel_hi:[1,0]
	v_pk_mul_f32 v[158:159], v[158:159], v[130:131] op_sel_hi:[1,0]
	v_cvt_pk_bf16_f32 v130, v154, v155
	v_cvt_pk_bf16_f32 v131, v132, v133
	v_cvt_pk_bf16_f32 v133, v156, v157
	v_pk_mul_f32 v[154:155], v[92:93], v[84:85]
	v_cvt_pk_bf16_f32 v132, v158, v159
	global_store_dwordx4 v[134:135], v[130:133], off offset:2048 sc1
	v_pk_mul_f32 v[156:157], v[90:91], v[82:83]
	v_pk_mul_f32 v[158:159], v[88:89], v[80:81]
	v_or_b32_e32 v130, 32, v152
	v_mad_i64_i32 v[130:131], s[82:83], v130, s19, v[128:129]
	v_lshl_add_u64 v[130:131], v[130:131], 0, s[96:97]
	v_lshl_add_u64 v[134:135], v[130:131], 0, v[136:137]
	v_fmamk_f32 v130, v169, 0x3a800000, v162
	v_cmp_gt_f32_e32 vcc, s40, v130
	v_mul_f32_e32 v131, 0x4b800000, v130
	v_pk_mul_f32 v[132:133], v[94:95], v[86:87]
	v_cndmask_b32_e32 v130, v130, v131, vcc
	v_rsq_f32_e32 v130, v130
	s_nop 0
	v_mul_f32_e32 v131, 0x45800000, v130
	v_cndmask_b32_e32 v130, v130, v131, vcc
	v_cndmask_b32_e64 v130, v130, 1.0, s[14:15]
	v_mul_f32_e32 v130, v130, v130
	v_pk_mul_f32 v[132:133], v[132:133], v[130:131] op_sel_hi:[1,0]
	v_pk_mul_f32 v[154:155], v[154:155], v[130:131] op_sel_hi:[1,0]
	v_pk_mul_f32 v[156:157], v[156:157], v[130:131] op_sel_hi:[1,0]
	v_pk_mul_f32 v[158:159], v[158:159], v[130:131] op_sel_hi:[1,0]
	v_cvt_pk_bf16_f32 v130, v154, v155
	v_cvt_pk_bf16_f32 v131, v132, v133
	v_cvt_pk_bf16_f32 v133, v156, v157
	v_pk_mul_f32 v[154:155], v[76:77], v[68:69]
	v_cvt_pk_bf16_f32 v132, v158, v159
	global_store_dwordx4 v[134:135], v[130:133], off offset:2048 sc1
	v_pk_mul_f32 v[156:157], v[74:75], v[66:67]
	v_pk_mul_f32 v[158:159], v[72:73], v[64:65]
	v_or_b32_e32 v130, 48, v152
	v_mad_i64_i32 v[130:131], s[82:83], v130, s19, v[128:129]
	v_lshl_add_u64 v[130:131], v[130:131], 0, s[96:97]
	v_lshl_add_u64 v[134:135], v[130:131], 0, v[136:137]
	v_fmamk_f32 v130, v170, 0x3a800000, v162
	v_cmp_gt_f32_e32 vcc, s40, v130
	v_mul_f32_e32 v131, 0x4b800000, v130
	v_pk_mul_f32 v[132:133], v[78:79], v[70:71]
	v_cndmask_b32_e32 v130, v130, v131, vcc
	v_rsq_f32_e32 v130, v130
	s_nop 0
	v_mul_f32_e32 v131, 0x45800000, v130
	v_cndmask_b32_e32 v130, v130, v131, vcc
	v_cndmask_b32_e64 v130, v130, 1.0, s[14:15]
	v_mul_f32_e32 v130, v130, v130
	v_pk_mul_f32 v[132:133], v[132:133], v[130:131] op_sel_hi:[1,0]
	v_pk_mul_f32 v[154:155], v[154:155], v[130:131] op_sel_hi:[1,0]
	v_pk_mul_f32 v[156:157], v[156:157], v[130:131] op_sel_hi:[1,0]
	v_pk_mul_f32 v[158:159], v[158:159], v[130:131] op_sel_hi:[1,0]
	v_cvt_pk_bf16_f32 v130, v154, v155
	v_cvt_pk_bf16_f32 v131, v132, v133
	v_cvt_pk_bf16_f32 v133, v156, v157
	v_pk_mul_f32 v[154:155], v[60:61], v[52:53]
	v_cvt_pk_bf16_f32 v132, v158, v159
	global_store_dwordx4 v[134:135], v[130:133], off offset:2048 sc1
	v_pk_mul_f32 v[156:157], v[58:59], v[50:51]
	v_pk_mul_f32 v[158:159], v[56:57], v[48:49]
	v_add_u32_e32 v130, 0x80, v152
	v_mad_i64_i32 v[130:131], s[82:83], v130, s19, v[128:129]
	v_lshl_add_u64 v[130:131], v[130:131], 0, s[96:97]
	v_lshl_add_u64 v[134:135], v[130:131], 0, v[136:137]
	v_fmamk_f32 v130, v171, 0x3a800000, v162
	v_cmp_gt_f32_e32 vcc, s40, v130
	v_mul_f32_e32 v131, 0x4b800000, v130
	v_pk_mul_f32 v[132:133], v[62:63], v[54:55]
	v_cndmask_b32_e32 v130, v130, v131, vcc
	v_rsq_f32_e32 v130, v130
	s_nop 0
	v_mul_f32_e32 v131, 0x45800000, v130
	v_cndmask_b32_e32 v130, v130, v131, vcc
	v_cndmask_b32_e64 v130, v130, 1.0, s[14:15]
	v_mul_f32_e32 v130, v130, v130
	v_pk_mul_f32 v[132:133], v[132:133], v[130:131] op_sel_hi:[1,0]
	v_pk_mul_f32 v[154:155], v[154:155], v[130:131] op_sel_hi:[1,0]
	v_pk_mul_f32 v[156:157], v[156:157], v[130:131] op_sel_hi:[1,0]
	v_pk_mul_f32 v[158:159], v[158:159], v[130:131] op_sel_hi:[1,0]
	v_cvt_pk_bf16_f32 v130, v154, v155
	v_cvt_pk_bf16_f32 v131, v132, v133
	v_cvt_pk_bf16_f32 v133, v156, v157
	v_pk_mul_f32 v[154:155], v[44:45], v[36:37]
	v_cvt_pk_bf16_f32 v132, v158, v159
	global_store_dwordx4 v[134:135], v[130:133], off offset:2048 sc1
	v_pk_mul_f32 v[156:157], v[42:43], v[34:35]
	v_pk_mul_f32 v[158:159], v[40:41], v[32:33]
	v_add_u32_e32 v130, 0x90, v152
	v_mad_i64_i32 v[130:131], s[82:83], v130, s19, v[128:129]
	v_lshl_add_u64 v[130:131], v[130:131], 0, s[96:97]
	v_lshl_add_u64 v[134:135], v[130:131], 0, v[136:137]
	v_fmamk_f32 v130, v172, 0x3a800000, v162
	v_cmp_gt_f32_e32 vcc, s40, v130
	v_mul_f32_e32 v131, 0x4b800000, v130
	v_pk_mul_f32 v[132:133], v[46:47], v[38:39]
	v_cndmask_b32_e32 v130, v130, v131, vcc
	v_rsq_f32_e32 v130, v130
	s_nop 0
	v_mul_f32_e32 v131, 0x45800000, v130
	v_cndmask_b32_e32 v130, v130, v131, vcc
	v_cndmask_b32_e64 v130, v130, 1.0, s[14:15]
	v_mul_f32_e32 v130, v130, v130
	v_pk_mul_f32 v[132:133], v[132:133], v[130:131] op_sel_hi:[1,0]
	v_pk_mul_f32 v[154:155], v[154:155], v[130:131] op_sel_hi:[1,0]
	v_pk_mul_f32 v[156:157], v[156:157], v[130:131] op_sel_hi:[1,0]
	v_pk_mul_f32 v[158:159], v[158:159], v[130:131] op_sel_hi:[1,0]
	v_cvt_pk_bf16_f32 v130, v154, v155
	v_cvt_pk_bf16_f32 v131, v132, v133
	v_cvt_pk_bf16_f32 v133, v156, v157
	v_pk_mul_f32 v[154:155], v[28:29], v[20:21]
	v_cvt_pk_bf16_f32 v132, v158, v159
	global_store_dwordx4 v[134:135], v[130:133], off offset:2048 sc1
	v_pk_mul_f32 v[156:157], v[26:27], v[18:19]
	v_pk_mul_f32 v[158:159], v[24:25], v[16:17]
	v_add_u32_e32 v130, 0xa0, v152
	v_mad_i64_i32 v[130:131], s[82:83], v130, s19, v[128:129]
	v_lshl_add_u64 v[130:131], v[130:131], 0, s[96:97]
	v_lshl_add_u64 v[134:135], v[130:131], 0, v[136:137]
	v_fmamk_f32 v130, v174, 0x3a800000, v162
	v_cmp_gt_f32_e32 vcc, s40, v130
	v_mul_f32_e32 v131, 0x4b800000, v130
	v_pk_mul_f32 v[132:133], v[30:31], v[22:23]
	v_cndmask_b32_e32 v130, v130, v131, vcc
	v_rsq_f32_e32 v130, v130
	s_nop 0
	v_mul_f32_e32 v131, 0x45800000, v130
	v_cndmask_b32_e32 v130, v130, v131, vcc
	v_cndmask_b32_e64 v130, v130, 1.0, s[14:15]
	v_mul_f32_e32 v130, v130, v130
	v_pk_mul_f32 v[132:133], v[132:133], v[130:131] op_sel_hi:[1,0]
	v_pk_mul_f32 v[154:155], v[154:155], v[130:131] op_sel_hi:[1,0]
	v_pk_mul_f32 v[156:157], v[156:157], v[130:131] op_sel_hi:[1,0]
	v_pk_mul_f32 v[158:159], v[158:159], v[130:131] op_sel_hi:[1,0]
	v_cvt_pk_bf16_f32 v130, v154, v155
	v_cvt_pk_bf16_f32 v131, v132, v133
	v_cvt_pk_bf16_f32 v133, v156, v157
	v_pk_mul_f32 v[154:155], v[10:11], v[2:3]
	v_cvt_pk_bf16_f32 v132, v158, v159
	global_store_dwordx4 v[134:135], v[130:133], off offset:2048 sc1
	v_pk_mul_f32 v[134:135], v[12:13], v[4:5]
	v_pk_mul_f32 v[156:157], v[8:9], v[0:1]
	v_add_u32_e32 v130, 0xb0, v152
	v_mad_i64_i32 v[128:129], s[82:83], v130, s19, v[128:129]
	v_lshl_add_u64 v[128:129], v[128:129], 0, s[96:97]
	v_lshl_add_u64 v[132:133], v[128:129], 0, v[136:137]
	v_fmamk_f32 v128, v173, 0x3a800000, v162
	v_cmp_gt_f32_e32 vcc, s40, v128
	v_mul_f32_e32 v129, 0x4b800000, v128
	v_pk_mul_f32 v[130:131], v[14:15], v[6:7]
	v_cndmask_b32_e32 v128, v128, v129, vcc
	v_rsq_f32_e32 v128, v128
	s_nop 0
	v_mul_f32_e32 v129, 0x45800000, v128
	v_cndmask_b32_e32 v128, v128, v129, vcc
	v_cndmask_b32_e64 v128, v128, 1.0, s[14:15]
	v_mul_f32_e32 v128, v128, v128
	v_pk_mul_f32 v[130:131], v[130:131], v[128:129] op_sel_hi:[1,0]
	v_pk_mul_f32 v[134:135], v[134:135], v[128:129] op_sel_hi:[1,0]
	v_pk_mul_f32 v[154:155], v[154:155], v[128:129] op_sel_hi:[1,0]
	v_pk_mul_f32 v[156:157], v[156:157], v[128:129] op_sel_hi:[1,0]
	v_cvt_pk_bf16_f32 v128, v134, v135
	v_cvt_pk_bf16_f32 v129, v130, v131
	v_cvt_pk_bf16_f32 v131, v154, v155
	s_nop 0
	v_cvt_pk_bf16_f32 v130, v156, v157
	global_store_dwordx4 v[132:133], v[128:131], off offset:2048 sc1

.LBB0_209:
	s_waitcnt vmcnt(0)
	v_fmamk_f32 v132, v167, 0x3a800000, v162
	v_mul_f32_e32 v133, 0x4b800000, v132
	v_cmp_gt_f32_e32 vcc, s40, v132
	v_mul_lo_u32 v130, s1, v152
	s_waitcnt lgkmcnt(0)
	v_mul_lo_u32 v131, s0, v153
	v_cndmask_b32_e32 v132, v132, v133, vcc
	v_rsq_f32_e32 v132, v132
	v_mad_u64_u32 v[128:129], s[18:19], s0, v152, 0
	v_add3_u32 v129, v129, v131, v130
	v_lshl_add_u64 v[128:129], v[128:129], 1, s[28:29]
	v_lshl_add_u64 v[158:159], v[154:155], 1, v[128:129]
	v_mul_f32_e32 v128, 0x45800000, v132
	v_cndmask_b32_e32 v128, v132, v128, vcc
	v_cndmask_b32_e64 v160, v128, 1.0, s[14:15]
	v_cmp_ne_u64_e32 vcc, 0, v[156:157]
	v_pk_mul_f32 v[130:131], v[126:127], v[160:161] op_sel_hi:[1,0]
	v_pk_mul_f32 v[128:129], v[124:125], v[160:161] op_sel_hi:[1,0]
	v_pk_mul_f32 v[134:135], v[122:123], v[160:161] op_sel_hi:[1,0]
	v_pk_mul_f32 v[132:133], v[120:121], v[160:161] op_sel_hi:[1,0]
	v_cvt_pk_bf16_f32 v180, v128, v129
	v_cvt_pk_bf16_f32 v181, v130, v131
	v_cvt_pk_bf16_f32 v183, v134, v135
	s_nop 0
	v_cvt_pk_bf16_f32 v182, v132, v133
	global_store_dwordx4 v[158:159], v[180:183], off sc1
	s_and_saveexec_b64 s[18:19], vcc
	s_cbranch_execz .LBB0_211
	global_store_dwordx4 v[156:157], v[128:131], off sc1
	global_store_dwordx4 v[156:157], v[132:135], off offset:16 sc1
.LBB0_211:
	s_or_b64 exec, exec, s[18:19]
	v_mov_b32_e32 v161, v160
	v_mov_b32_e32 v132, v160
	v_mov_b32_e32 v133, v160
	v_pk_mul_f32 v[130:131], v[118:119], v[132:133]
	v_pk_mul_f32 v[128:129], v[116:117], v[160:161]
	v_pk_mul_f32 v[134:135], v[114:115], v[132:133]
	v_pk_mul_f32 v[132:133], v[112:113], v[160:161]
	v_cvt_pk_bf16_f32 v180, v128, v129
	v_cvt_pk_bf16_f32 v181, v130, v131
	v_cvt_pk_bf16_f32 v183, v134, v135
	s_nop 0
	v_cvt_pk_bf16_f32 v182, v132, v133
	global_store_dwordx4 v[158:159], v[180:183], off offset:256 sc1
	s_and_saveexec_b64 s[18:19], vcc
	s_cbranch_execz .LBB0_213
	global_store_dwordx4 v[156:157], v[128:131], off offset:512 sc1
	global_store_dwordx4 v[156:157], v[132:135], off offset:528 sc1

.LBB0_230:
	v_fmamk_f32 v132, v168, 0x3a800000, v162
	v_mul_f32_e32 v133, 0x4b800000, v132
	v_cmp_gt_f32_e32 vcc, s40, v132
	v_mul_lo_u32 v130, s1, v128
	v_mul_lo_u32 v131, s0, v129
	v_cndmask_b32_e32 v132, v132, v133, vcc
	v_rsq_f32_e32 v132, v132
	v_mad_u64_u32 v[128:129], s[18:19], s0, v128, 0
	v_add3_u32 v129, v129, v131, v130
	v_lshl_add_u64 v[128:129], v[128:129], 1, s[28:29]
	v_lshl_add_u64 v[158:159], v[154:155], 1, v[128:129]
	v_mul_f32_e32 v128, 0x45800000, v132
	v_cndmask_b32_e32 v128, v132, v128, vcc
	v_cndmask_b32_e64 v160, v128, 1.0, s[14:15]
	v_cmp_ne_u64_e32 vcc, 0, v[156:157]
	v_pk_mul_f32 v[130:131], v[110:111], v[160:161] op_sel_hi:[1,0]
	v_pk_mul_f32 v[128:129], v[108:109], v[160:161] op_sel_hi:[1,0]
	v_pk_mul_f32 v[134:135], v[106:107], v[160:161] op_sel_hi:[1,0]
	v_pk_mul_f32 v[132:133], v[104:105], v[160:161] op_sel_hi:[1,0]
	v_cvt_pk_bf16_f32 v180, v128, v129
	v_cvt_pk_bf16_f32 v181, v130, v131
	v_cvt_pk_bf16_f32 v183, v134, v135
	s_nop 0
	v_cvt_pk_bf16_f32 v182, v132, v133
	global_store_dwordx4 v[158:159], v[180:183], off sc1
	s_and_saveexec_b64 s[18:19], vcc
	s_cbranch_execz .LBB0_232
	global_store_dwordx4 v[156:157], v[128:131], off sc1
	global_store_dwordx4 v[156:157], v[132:135], off offset:16 sc1
.LBB0_232:
	s_or_b64 exec, exec, s[18:19]
	v_mov_b32_e32 v161, v160
	v_mov_b32_e32 v132, v160
	v_mov_b32_e32 v133, v160
	v_pk_mul_f32 v[130:131], v[102:103], v[132:133]
	v_pk_mul_f32 v[128:129], v[100:101], v[160:161]
	v_pk_mul_f32 v[134:135], v[98:99], v[132:133]
	v_pk_mul_f32 v[132:133], v[96:97], v[160:161]
	v_cvt_pk_bf16_f32 v180, v128, v129
	v_cvt_pk_bf16_f32 v181, v130, v131
	v_cvt_pk_bf16_f32 v183, v134, v135
	s_nop 0
	v_cvt_pk_bf16_f32 v182, v132, v133
	global_store_dwordx4 v[158:159], v[180:183], off offset:256 sc1
	s_and_saveexec_b64 s[18:19], vcc
	s_cbranch_execz .LBB0_234
	global_store_dwordx4 v[156:157], v[128:131], off offset:512 sc1
	global_store_dwordx4 v[156:157], v[132:135], off offset:528 sc1

.LBB0_251:
	v_fmamk_f32 v132, v169, 0x3a800000, v162
	v_mul_f32_e32 v133, 0x4b800000, v132
	v_cmp_gt_f32_e32 vcc, s40, v132
	v_mul_lo_u32 v130, s1, v128
	v_mul_lo_u32 v131, s0, v129
	v_cndmask_b32_e32 v132, v132, v133, vcc
	v_rsq_f32_e32 v132, v132
	v_mad_u64_u32 v[128:129], s[18:19], s0, v128, 0
	v_add3_u32 v129, v129, v131, v130
	v_lshl_add_u64 v[128:129], v[128:129], 1, s[28:29]
	v_lshl_add_u64 v[158:159], v[154:155], 1, v[128:129]
	v_mul_f32_e32 v128, 0x45800000, v132
	v_cndmask_b32_e32 v128, v132, v128, vcc
	v_cndmask_b32_e64 v160, v128, 1.0, s[14:15]
	v_cmp_ne_u64_e32 vcc, 0, v[156:157]
	v_pk_mul_f32 v[130:131], v[94:95], v[160:161] op_sel_hi:[1,0]
	v_pk_mul_f32 v[128:129], v[92:93], v[160:161] op_sel_hi:[1,0]
	v_pk_mul_f32 v[134:135], v[90:91], v[160:161] op_sel_hi:[1,0]
	v_pk_mul_f32 v[132:133], v[88:89], v[160:161] op_sel_hi:[1,0]
	v_cvt_pk_bf16_f32 v180, v128, v129
	v_cvt_pk_bf16_f32 v181, v130, v131
	v_cvt_pk_bf16_f32 v183, v134, v135
	s_nop 0
	v_cvt_pk_bf16_f32 v182, v132, v133
	global_store_dwordx4 v[158:159], v[180:183], off sc1
	s_and_saveexec_b64 s[18:19], vcc
	s_cbranch_execz .LBB0_253
	global_store_dwordx4 v[156:157], v[128:131], off sc1
	global_store_dwordx4 v[156:157], v[132:135], off offset:16 sc1
.LBB0_253:
	s_or_b64 exec, exec, s[18:19]
	v_mov_b32_e32 v161, v160
	v_mov_b32_e32 v132, v160
	v_mov_b32_e32 v133, v160
	v_pk_mul_f32 v[130:131], v[86:87], v[132:133]
	v_pk_mul_f32 v[128:129], v[84:85], v[160:161]
	v_pk_mul_f32 v[134:135], v[82:83], v[132:133]
	v_pk_mul_f32 v[132:133], v[80:81], v[160:161]
	v_cvt_pk_bf16_f32 v180, v128, v129
	v_cvt_pk_bf16_f32 v181, v130, v131
	v_cvt_pk_bf16_f32 v183, v134, v135
	s_nop 0
	v_cvt_pk_bf16_f32 v182, v132, v133
	global_store_dwordx4 v[158:159], v[180:183], off offset:256 sc1
	s_and_saveexec_b64 s[18:19], vcc
	s_cbranch_execz .LBB0_255
	global_store_dwordx4 v[156:157], v[128:131], off offset:512 sc1
	global_store_dwordx4 v[156:157], v[132:135], off offset:528 sc1

.LBB0_272:
	v_fmamk_f32 v132, v170, 0x3a800000, v162
	v_mul_f32_e32 v133, 0x4b800000, v132
	v_cmp_gt_f32_e32 vcc, s40, v132
	v_mul_lo_u32 v130, s1, v128
	v_mul_lo_u32 v131, s0, v129
	v_cndmask_b32_e32 v132, v132, v133, vcc
	v_rsq_f32_e32 v132, v132
	v_mad_u64_u32 v[128:129], s[18:19], s0, v128, 0
	v_add3_u32 v129, v129, v131, v130
	v_lshl_add_u64 v[128:129], v[128:129], 1, s[28:29]
	v_lshl_add_u64 v[158:159], v[154:155], 1, v[128:129]
	v_mul_f32_e32 v128, 0x45800000, v132
	v_cndmask_b32_e32 v128, v132, v128, vcc
	v_cndmask_b32_e64 v160, v128, 1.0, s[14:15]
	v_cmp_ne_u64_e32 vcc, 0, v[156:157]
	v_pk_mul_f32 v[130:131], v[78:79], v[160:161] op_sel_hi:[1,0]
	v_pk_mul_f32 v[128:129], v[76:77], v[160:161] op_sel_hi:[1,0]
	v_pk_mul_f32 v[134:135], v[74:75], v[160:161] op_sel_hi:[1,0]
	v_pk_mul_f32 v[132:133], v[72:73], v[160:161] op_sel_hi:[1,0]
	v_cvt_pk_bf16_f32 v180, v128, v129
	v_cvt_pk_bf16_f32 v181, v130, v131
	v_cvt_pk_bf16_f32 v183, v134, v135
	s_nop 0
	v_cvt_pk_bf16_f32 v182, v132, v133
	global_store_dwordx4 v[158:159], v[180:183], off sc1
	s_and_saveexec_b64 s[18:19], vcc
	s_cbranch_execz .LBB0_274
	global_store_dwordx4 v[156:157], v[128:131], off sc1
	global_store_dwordx4 v[156:157], v[132:135], off offset:16 sc1
.LBB0_274:
	s_or_b64 exec, exec, s[18:19]
	v_mov_b32_e32 v161, v160
	v_mov_b32_e32 v132, v160
	v_mov_b32_e32 v133, v160
	v_pk_mul_f32 v[130:131], v[70:71], v[132:133]
	v_pk_mul_f32 v[128:129], v[68:69], v[160:161]
	v_pk_mul_f32 v[134:135], v[66:67], v[132:133]
	v_pk_mul_f32 v[132:133], v[64:65], v[160:161]
	v_cvt_pk_bf16_f32 v180, v128, v129
	v_cvt_pk_bf16_f32 v181, v130, v131
	v_cvt_pk_bf16_f32 v183, v134, v135
	s_nop 0
	v_cvt_pk_bf16_f32 v182, v132, v133
	global_store_dwordx4 v[158:159], v[180:183], off offset:256 sc1
	s_and_saveexec_b64 s[18:19], vcc
	s_cbranch_execz .LBB0_276
	global_store_dwordx4 v[156:157], v[128:131], off offset:512 sc1
	global_store_dwordx4 v[156:157], v[132:135], off offset:528 sc1

.LBB0_293:
	v_fmamk_f32 v132, v171, 0x3a800000, v162
	v_mul_f32_e32 v133, 0x4b800000, v132
	v_cmp_gt_f32_e32 vcc, s40, v132
	v_mul_lo_u32 v130, s1, v128
	v_mul_lo_u32 v131, s0, v129
	v_cndmask_b32_e32 v132, v132, v133, vcc
	v_rsq_f32_e32 v132, v132
	v_mad_u64_u32 v[128:129], s[18:19], s0, v128, 0
	v_add3_u32 v129, v129, v131, v130
	v_lshl_add_u64 v[128:129], v[128:129], 1, s[28:29]
	v_lshl_add_u64 v[158:159], v[154:155], 1, v[128:129]
	v_mul_f32_e32 v128, 0x45800000, v132
	v_cndmask_b32_e32 v128, v132, v128, vcc
	v_cndmask_b32_e64 v160, v128, 1.0, s[14:15]
	v_cmp_ne_u64_e32 vcc, 0, v[156:157]
	v_pk_mul_f32 v[130:131], v[62:63], v[160:161] op_sel_hi:[1,0]
	v_pk_mul_f32 v[128:129], v[60:61], v[160:161] op_sel_hi:[1,0]
	v_pk_mul_f32 v[134:135], v[58:59], v[160:161] op_sel_hi:[1,0]
	v_pk_mul_f32 v[132:133], v[56:57], v[160:161] op_sel_hi:[1,0]
	v_cvt_pk_bf16_f32 v180, v128, v129
	v_cvt_pk_bf16_f32 v181, v130, v131
	v_cvt_pk_bf16_f32 v183, v134, v135
	s_nop 0
	v_cvt_pk_bf16_f32 v182, v132, v133
	global_store_dwordx4 v[158:159], v[180:183], off sc1
	s_and_saveexec_b64 s[18:19], vcc
	s_cbranch_execz .LBB0_295
	global_store_dwordx4 v[156:157], v[128:131], off sc1
	global_store_dwordx4 v[156:157], v[132:135], off offset:16 sc1
.LBB0_295:
	s_or_b64 exec, exec, s[18:19]
	v_mov_b32_e32 v161, v160
	v_mov_b32_e32 v132, v160
	v_mov_b32_e32 v133, v160
	v_pk_mul_f32 v[130:131], v[54:55], v[132:133]
	v_pk_mul_f32 v[128:129], v[52:53], v[160:161]
	v_pk_mul_f32 v[134:135], v[50:51], v[132:133]
	v_pk_mul_f32 v[132:133], v[48:49], v[160:161]
	v_cvt_pk_bf16_f32 v180, v128, v129
	v_cvt_pk_bf16_f32 v181, v130, v131
	v_cvt_pk_bf16_f32 v183, v134, v135
	s_nop 0
	v_cvt_pk_bf16_f32 v182, v132, v133
	global_store_dwordx4 v[158:159], v[180:183], off offset:256 sc1
	s_and_saveexec_b64 s[18:19], vcc
	s_cbranch_execz .LBB0_297
	global_store_dwordx4 v[156:157], v[128:131], off offset:512 sc1
	global_store_dwordx4 v[156:157], v[132:135], off offset:528 sc1

.LBB0_314:
	v_fmamk_f32 v132, v172, 0x3a800000, v162
	v_mul_f32_e32 v133, 0x4b800000, v132
	v_cmp_gt_f32_e32 vcc, s40, v132
	v_mul_lo_u32 v130, s1, v128
	v_mul_lo_u32 v131, s0, v129
	v_cndmask_b32_e32 v132, v132, v133, vcc
	v_rsq_f32_e32 v132, v132
	v_mad_u64_u32 v[128:129], s[18:19], s0, v128, 0
	v_add3_u32 v129, v129, v131, v130
	v_lshl_add_u64 v[128:129], v[128:129], 1, s[28:29]
	v_lshl_add_u64 v[158:159], v[154:155], 1, v[128:129]
	v_mul_f32_e32 v128, 0x45800000, v132
	v_cndmask_b32_e32 v128, v132, v128, vcc
	v_cndmask_b32_e64 v160, v128, 1.0, s[14:15]
	v_cmp_ne_u64_e32 vcc, 0, v[156:157]
	v_pk_mul_f32 v[130:131], v[46:47], v[160:161] op_sel_hi:[1,0]
	v_pk_mul_f32 v[128:129], v[44:45], v[160:161] op_sel_hi:[1,0]
	v_pk_mul_f32 v[134:135], v[42:43], v[160:161] op_sel_hi:[1,0]
	v_pk_mul_f32 v[132:133], v[40:41], v[160:161] op_sel_hi:[1,0]
	v_cvt_pk_bf16_f32 v180, v128, v129
	v_cvt_pk_bf16_f32 v181, v130, v131
	v_cvt_pk_bf16_f32 v183, v134, v135
	s_nop 0
	v_cvt_pk_bf16_f32 v182, v132, v133
	global_store_dwordx4 v[158:159], v[180:183], off sc1
	s_and_saveexec_b64 s[18:19], vcc
	s_cbranch_execz .LBB0_316
	global_store_dwordx4 v[156:157], v[128:131], off sc1
	global_store_dwordx4 v[156:157], v[132:135], off offset:16 sc1
.LBB0_316:
	s_or_b64 exec, exec, s[18:19]
	v_mov_b32_e32 v161, v160
	v_mov_b32_e32 v132, v160
	v_mov_b32_e32 v133, v160
	v_pk_mul_f32 v[130:131], v[38:39], v[132:133]
	v_pk_mul_f32 v[128:129], v[36:37], v[160:161]
	v_pk_mul_f32 v[134:135], v[34:35], v[132:133]
	v_pk_mul_f32 v[132:133], v[32:33], v[160:161]
	v_cvt_pk_bf16_f32 v180, v128, v129
	v_cvt_pk_bf16_f32 v181, v130, v131
	v_cvt_pk_bf16_f32 v183, v134, v135
	s_nop 0
	v_cvt_pk_bf16_f32 v182, v132, v133
	global_store_dwordx4 v[158:159], v[180:183], off offset:256 sc1
	s_and_saveexec_b64 s[18:19], vcc
	s_cbranch_execz .LBB0_318
	global_store_dwordx4 v[156:157], v[128:131], off offset:512 sc1
	global_store_dwordx4 v[156:157], v[132:135], off offset:528 sc1

.LBB0_335:
	v_fmamk_f32 v132, v174, 0x3a800000, v162
	v_mul_f32_e32 v133, 0x4b800000, v132
	v_cmp_gt_f32_e32 vcc, s40, v132
	v_mul_lo_u32 v130, s1, v128
	v_mul_lo_u32 v131, s0, v129
	v_cndmask_b32_e32 v132, v132, v133, vcc
	v_rsq_f32_e32 v132, v132
	v_mad_u64_u32 v[128:129], s[18:19], s0, v128, 0
	v_add3_u32 v129, v129, v131, v130
	v_lshl_add_u64 v[128:129], v[128:129], 1, s[28:29]
	v_lshl_add_u64 v[158:159], v[154:155], 1, v[128:129]
	v_mul_f32_e32 v128, 0x45800000, v132
	v_cndmask_b32_e32 v128, v132, v128, vcc
	v_cndmask_b32_e64 v160, v128, 1.0, s[14:15]
	v_cmp_ne_u64_e32 vcc, 0, v[156:157]
	v_pk_mul_f32 v[130:131], v[30:31], v[160:161] op_sel_hi:[1,0]
	v_pk_mul_f32 v[128:129], v[28:29], v[160:161] op_sel_hi:[1,0]
	v_pk_mul_f32 v[134:135], v[26:27], v[160:161] op_sel_hi:[1,0]
	v_pk_mul_f32 v[132:133], v[24:25], v[160:161] op_sel_hi:[1,0]
	v_cvt_pk_bf16_f32 v180, v128, v129
	v_cvt_pk_bf16_f32 v181, v130, v131
	v_cvt_pk_bf16_f32 v183, v134, v135
	s_nop 0
	v_cvt_pk_bf16_f32 v182, v132, v133
	global_store_dwordx4 v[158:159], v[180:183], off sc1
	s_and_saveexec_b64 s[18:19], vcc
	s_cbranch_execz .LBB0_337
	global_store_dwordx4 v[156:157], v[128:131], off sc1
	global_store_dwordx4 v[156:157], v[132:135], off offset:16 sc1
.LBB0_337:
	s_or_b64 exec, exec, s[18:19]
	v_mov_b32_e32 v161, v160
	v_mov_b32_e32 v132, v160
	v_mov_b32_e32 v133, v160
	v_pk_mul_f32 v[130:131], v[22:23], v[132:133]
	v_pk_mul_f32 v[128:129], v[20:21], v[160:161]
	v_pk_mul_f32 v[134:135], v[18:19], v[132:133]
	v_pk_mul_f32 v[132:133], v[16:17], v[160:161]
	v_cvt_pk_bf16_f32 v180, v128, v129
	v_cvt_pk_bf16_f32 v181, v130, v131
	v_cvt_pk_bf16_f32 v183, v134, v135
	s_nop 0
	v_cvt_pk_bf16_f32 v182, v132, v133
	global_store_dwordx4 v[158:159], v[180:183], off offset:256 sc1
	s_and_saveexec_b64 s[18:19], vcc
	s_cbranch_execz .LBB0_339
	global_store_dwordx4 v[156:157], v[128:131], off offset:512 sc1
	global_store_dwordx4 v[156:157], v[132:135], off offset:528 sc1

.LBB0_356:
	v_fmamk_f32 v132, v173, 0x3a800000, v162
	v_mul_f32_e32 v133, 0x4b800000, v132
	v_cmp_gt_f32_e32 vcc, s40, v132
	v_mul_lo_u32 v130, s1, v128
	v_mul_lo_u32 v131, s0, v129
	v_cndmask_b32_e32 v132, v132, v133, vcc
	v_rsq_f32_e32 v132, v132
	v_mad_u64_u32 v[128:129], s[18:19], s0, v128, 0
	v_add3_u32 v129, v129, v131, v130
	v_lshl_add_u64 v[128:129], v[128:129], 1, s[28:29]
	v_lshl_add_u64 v[154:155], v[154:155], 1, v[128:129]
	v_mul_f32_e32 v128, 0x45800000, v132
	v_cndmask_b32_e32 v128, v132, v128, vcc
	v_cndmask_b32_e64 v158, v128, 1.0, s[14:15]
	v_cmp_ne_u64_e32 vcc, 0, v[156:157]
	v_pk_mul_f32 v[130:131], v[14:15], v[158:159] op_sel_hi:[1,0]
	v_pk_mul_f32 v[128:129], v[12:13], v[158:159] op_sel_hi:[1,0]
	v_pk_mul_f32 v[134:135], v[10:11], v[158:159] op_sel_hi:[1,0]
	v_pk_mul_f32 v[132:133], v[8:9], v[158:159] op_sel_hi:[1,0]
	v_cvt_pk_bf16_f32 v180, v128, v129
	v_cvt_pk_bf16_f32 v181, v130, v131
	v_cvt_pk_bf16_f32 v183, v134, v135
	s_nop 0
	v_cvt_pk_bf16_f32 v182, v132, v133
	global_store_dwordx4 v[154:155], v[180:183], off sc1
	s_and_saveexec_b64 s[18:19], vcc
	s_cbranch_execz .LBB0_358
	global_store_dwordx4 v[156:157], v[128:131], off sc1
	global_store_dwordx4 v[156:157], v[132:135], off offset:16 sc1
.LBB0_358:
	s_or_b64 exec, exec, s[18:19]
	v_mov_b32_e32 v159, v158
	v_mov_b32_e32 v132, v158
	v_mov_b32_e32 v133, v158
	v_pk_mul_f32 v[130:131], v[6:7], v[132:133]
	v_pk_mul_f32 v[128:129], v[4:5], v[158:159]
	v_pk_mul_f32 v[134:135], v[2:3], v[132:133]
	v_pk_mul_f32 v[132:133], v[0:1], v[158:159]
	v_cvt_pk_bf16_f32 v158, v128, v129
	v_cvt_pk_bf16_f32 v159, v130, v131
	v_cvt_pk_bf16_f32 v161, v134, v135
	s_nop 0
	v_cvt_pk_bf16_f32 v160, v132, v133
	global_store_dwordx4 v[154:155], v[158:161], off offset:256 sc1
	s_and_saveexec_b64 s[18:19], vcc
	s_cbranch_execz .LBB0_360
	global_store_dwordx4 v[156:157], v[128:131], off offset:512 sc1
	global_store_dwordx4 v[156:157], v[132:135], off offset:528 sc1

.LBB0_361:
	s_waitcnt vmcnt(0) lgkmcnt(0)
	v_mul_lo_u32 v128, v152, s42
	s_lshl_b32 s18, s47, 8
	v_lshl_add_u32 v129, v146, 1, s18
	v_add_u32_e32 v128, v128, v129
	v_mov_b32_e32 v160, 1.0
	v_mov_b32_e32 v161, 1.0
	v_fmamk_f32 v132, v167, 0x3a800000, v162
	v_cmp_gt_f32_e32 vcc, s40, v132
	v_mul_f32_e32 v133, 0x4b800000, v132
	v_pk_mul_f32 v[116:117], v[124:125], v[116:117]
	v_pk_mul_f32 v[118:119], v[126:127], v[118:119]
	v_cndmask_b32_e32 v132, v132, v133, vcc
	v_rsq_f32_e32 v132, v132
	v_pk_mul_f32 v[112:113], v[120:121], v[112:113]
	v_pk_mul_f32 v[114:115], v[122:123], v[114:115]
	v_mul_f32_e32 v133, 0x45800000, v132
	v_cndmask_b32_e32 v132, v132, v133, vcc
	v_cndmask_b32_e64 v132, v132, 1.0, s[14:15]
	v_mul_f32_e32 v130, 0xbfb8aa3b, v132
	v_mul_f32_e32 v134, v132, v132
	v_pk_mul_f32 v[124:125], v[124:125], v[130:131] op_sel_hi:[1,0]
	v_pk_mul_f32 v[126:127], v[126:127], v[130:131] op_sel_hi:[1,0]
	v_pk_mul_f32 v[120:121], v[120:121], v[130:131] op_sel_hi:[1,0]
	v_pk_mul_f32 v[122:123], v[122:123], v[130:131] op_sel_hi:[1,0]
	v_exp_f32_e32 v124, v124
	v_exp_f32_e32 v125, v125
	v_exp_f32_e32 v126, v126
	v_exp_f32_e32 v127, v127
	v_exp_f32_e32 v120, v120
	v_exp_f32_e32 v121, v121
	v_exp_f32_e32 v122, v122
	v_exp_f32_e32 v123, v123
	v_pk_add_f32 v[124:125], v[124:125], v[160:161]
	v_pk_add_f32 v[126:127], v[126:127], v[160:161]
	v_pk_add_f32 v[120:121], v[120:121], v[160:161]
	v_pk_add_f32 v[122:123], v[122:123], v[160:161]
	v_rcp_f32_e32 v124, v124
	v_rcp_f32_e32 v125, v125
	v_rcp_f32_e32 v126, v126
	v_rcp_f32_e32 v127, v127
	v_rcp_f32_e32 v120, v120
	v_rcp_f32_e32 v121, v121
	v_rcp_f32_e32 v122, v122
	v_rcp_f32_e32 v123, v123
	v_pk_mul_f32 v[116:117], v[116:117], v[134:135] op_sel_hi:[1,0]
	v_pk_mul_f32 v[118:119], v[118:119], v[134:135] op_sel_hi:[1,0]
	v_pk_mul_f32 v[112:113], v[112:113], v[134:135] op_sel_hi:[1,0]
	v_pk_mul_f32 v[114:115], v[114:115], v[134:135] op_sel_hi:[1,0]
	v_pk_mul_f32 v[116:117], v[116:117], v[124:125]
	v_pk_mul_f32 v[118:119], v[118:119], v[126:127]
	v_pk_mul_f32 v[112:113], v[112:113], v[120:121]
	v_pk_mul_f32 v[114:115], v[114:115], v[122:123]
	v_cvt_pk_bf16_f32 v124, v116, v117
	v_cvt_pk_bf16_f32 v125, v118, v119
	v_cvt_pk_bf16_f32 v126, v112, v113
	v_cvt_pk_bf16_f32 v127, v114, v115
	global_store_dwordx4 v128, v[124:127], s[28:29] sc1
	v_fmamk_f32 v132, v168, 0x3a800000, v162
	v_cmp_gt_f32_e32 vcc, s40, v132
	v_mul_f32_e32 v133, 0x4b800000, v132
	v_pk_mul_f32 v[100:101], v[108:109], v[100:101]
	v_pk_mul_f32 v[102:103], v[110:111], v[102:103]
	v_cndmask_b32_e32 v132, v132, v133, vcc
	v_rsq_f32_e32 v132, v132
	v_pk_mul_f32 v[96:97], v[104:105], v[96:97]
	v_pk_mul_f32 v[98:99], v[106:107], v[98:99]
	v_mul_f32_e32 v133, 0x45800000, v132
	v_cndmask_b32_e32 v132, v132, v133, vcc
	v_cndmask_b32_e64 v132, v132, 1.0, s[14:15]
	v_mul_f32_e32 v130, 0xbfb8aa3b, v132
	v_mul_f32_e32 v134, v132, v132
	v_pk_mul_f32 v[108:109], v[108:109], v[130:131] op_sel_hi:[1,0]
	v_pk_mul_f32 v[110:111], v[110:111], v[130:131] op_sel_hi:[1,0]
	v_pk_mul_f32 v[104:105], v[104:105], v[130:131] op_sel_hi:[1,0]
	v_pk_mul_f32 v[106:107], v[106:107], v[130:131] op_sel_hi:[1,0]
	v_exp_f32_e32 v108, v108
	v_exp_f32_e32 v109, v109
	v_exp_f32_e32 v110, v110
	v_exp_f32_e32 v111, v111
	v_exp_f32_e32 v104, v104
	v_exp_f32_e32 v105, v105
	v_exp_f32_e32 v106, v106
	v_exp_f32_e32 v107, v107
	v_pk_add_f32 v[108:109], v[108:109], v[160:161]
	v_pk_add_f32 v[110:111], v[110:111], v[160:161]
	v_pk_add_f32 v[104:105], v[104:105], v[160:161]
	v_pk_add_f32 v[106:107], v[106:107], v[160:161]
	v_rcp_f32_e32 v108, v108
	v_rcp_f32_e32 v109, v109
	v_rcp_f32_e32 v110, v110
	v_rcp_f32_e32 v111, v111
	v_rcp_f32_e32 v104, v104
	v_rcp_f32_e32 v105, v105
	v_rcp_f32_e32 v106, v106
	v_rcp_f32_e32 v107, v107
	v_pk_mul_f32 v[100:101], v[100:101], v[134:135] op_sel_hi:[1,0]
	v_pk_mul_f32 v[102:103], v[102:103], v[134:135] op_sel_hi:[1,0]
	v_pk_mul_f32 v[96:97], v[96:97], v[134:135] op_sel_hi:[1,0]
	v_pk_mul_f32 v[98:99], v[98:99], v[134:135] op_sel_hi:[1,0]
	v_pk_mul_f32 v[100:101], v[100:101], v[108:109]
	v_pk_mul_f32 v[102:103], v[102:103], v[110:111]
	v_pk_mul_f32 v[96:97], v[96:97], v[104:105]
	v_pk_mul_f32 v[98:99], v[98:99], v[106:107]
	v_add_u32_e32 v129, 0x16000, v128
	v_cvt_pk_bf16_f32 v108, v100, v101
	v_cvt_pk_bf16_f32 v109, v102, v103
	v_cvt_pk_bf16_f32 v110, v96, v97
	v_cvt_pk_bf16_f32 v111, v98, v99
	global_store_dwordx4 v129, v[108:111], s[28:29] sc1
	v_fmamk_f32 v132, v169, 0x3a800000, v162
	v_cmp_gt_f32_e32 vcc, s40, v132
	v_mul_f32_e32 v133, 0x4b800000, v132
	v_pk_mul_f32 v[84:85], v[92:93], v[84:85]
	v_pk_mul_f32 v[86:87], v[94:95], v[86:87]
	v_cndmask_b32_e32 v132, v132, v133, vcc
	v_rsq_f32_e32 v132, v132
	v_pk_mul_f32 v[80:81], v[88:89], v[80:81]
	v_pk_mul_f32 v[82:83], v[90:91], v[82:83]
	v_mul_f32_e32 v133, 0x45800000, v132
	v_cndmask_b32_e32 v132, v132, v133, vcc
	v_cndmask_b32_e64 v132, v132, 1.0, s[14:15]
	v_mul_f32_e32 v130, 0xbfb8aa3b, v132
	v_mul_f32_e32 v134, v132, v132
	v_pk_mul_f32 v[92:93], v[92:93], v[130:131] op_sel_hi:[1,0]
	v_pk_mul_f32 v[94:95], v[94:95], v[130:131] op_sel_hi:[1,0]
	v_pk_mul_f32 v[88:89], v[88:89], v[130:131] op_sel_hi:[1,0]
	v_pk_mul_f32 v[90:91], v[90:91], v[130:131] op_sel_hi:[1,0]
	v_exp_f32_e32 v92, v92
	v_exp_f32_e32 v93, v93
	v_exp_f32_e32 v94, v94
	v_exp_f32_e32 v95, v95
	v_exp_f32_e32 v88, v88
	v_exp_f32_e32 v89, v89
	v_exp_f32_e32 v90, v90
	v_exp_f32_e32 v91, v91
	v_pk_add_f32 v[92:93], v[92:93], v[160:161]
	v_pk_add_f32 v[94:95], v[94:95], v[160:161]
	v_pk_add_f32 v[88:89], v[88:89], v[160:161]
	v_pk_add_f32 v[90:91], v[90:91], v[160:161]
	v_rcp_f32_e32 v92, v92
	v_rcp_f32_e32 v93, v93
	v_rcp_f32_e32 v94, v94
	v_rcp_f32_e32 v95, v95
	v_rcp_f32_e32 v88, v88
	v_rcp_f32_e32 v89, v89
	v_rcp_f32_e32 v90, v90
	v_rcp_f32_e32 v91, v91
	v_pk_mul_f32 v[84:85], v[84:85], v[134:135] op_sel_hi:[1,0]
	v_pk_mul_f32 v[86:87], v[86:87], v[134:135] op_sel_hi:[1,0]
	v_pk_mul_f32 v[80:81], v[80:81], v[134:135] op_sel_hi:[1,0]
	v_pk_mul_f32 v[82:83], v[82:83], v[134:135] op_sel_hi:[1,0]
	v_pk_mul_f32 v[84:85], v[84:85], v[92:93]
	v_pk_mul_f32 v[86:87], v[86:87], v[94:95]
	v_pk_mul_f32 v[80:81], v[80:81], v[88:89]
	v_pk_mul_f32 v[82:83], v[82:83], v[90:91]
	v_add_u32_e32 v129, 0x2c000, v128
	v_cvt_pk_bf16_f32 v92, v84, v85
	v_cvt_pk_bf16_f32 v93, v86, v87
	v_cvt_pk_bf16_f32 v94, v80, v81
	v_cvt_pk_bf16_f32 v95, v82, v83
	global_store_dwordx4 v129, v[92:95], s[28:29] sc1
	v_fmamk_f32 v132, v170, 0x3a800000, v162
	v_cmp_gt_f32_e32 vcc, s40, v132
	v_mul_f32_e32 v133, 0x4b800000, v132
	v_pk_mul_f32 v[68:69], v[76:77], v[68:69]
	v_pk_mul_f32 v[70:71], v[78:79], v[70:71]
	v_cndmask_b32_e32 v132, v132, v133, vcc
	v_rsq_f32_e32 v132, v132
	v_pk_mul_f32 v[64:65], v[72:73], v[64:65]
	v_pk_mul_f32 v[66:67], v[74:75], v[66:67]
	v_mul_f32_e32 v133, 0x45800000, v132
	v_cndmask_b32_e32 v132, v132, v133, vcc
	v_cndmask_b32_e64 v132, v132, 1.0, s[14:15]
	v_mul_f32_e32 v130, 0xbfb8aa3b, v132
	v_mul_f32_e32 v134, v132, v132
	v_pk_mul_f32 v[76:77], v[76:77], v[130:131] op_sel_hi:[1,0]
	v_pk_mul_f32 v[78:79], v[78:79], v[130:131] op_sel_hi:[1,0]
	v_pk_mul_f32 v[72:73], v[72:73], v[130:131] op_sel_hi:[1,0]
	v_pk_mul_f32 v[74:75], v[74:75], v[130:131] op_sel_hi:[1,0]
	v_exp_f32_e32 v76, v76
	v_exp_f32_e32 v77, v77
	v_exp_f32_e32 v78, v78
	v_exp_f32_e32 v79, v79
	v_exp_f32_e32 v72, v72
	v_exp_f32_e32 v73, v73
	v_exp_f32_e32 v74, v74
	v_exp_f32_e32 v75, v75
	v_pk_add_f32 v[76:77], v[76:77], v[160:161]
	v_pk_add_f32 v[78:79], v[78:79], v[160:161]
	v_pk_add_f32 v[72:73], v[72:73], v[160:161]
	v_pk_add_f32 v[74:75], v[74:75], v[160:161]
	v_rcp_f32_e32 v76, v76
	v_rcp_f32_e32 v77, v77
	v_rcp_f32_e32 v78, v78
	v_rcp_f32_e32 v79, v79
	v_rcp_f32_e32 v72, v72
	v_rcp_f32_e32 v73, v73
	v_rcp_f32_e32 v74, v74
	v_rcp_f32_e32 v75, v75
	v_pk_mul_f32 v[68:69], v[68:69], v[134:135] op_sel_hi:[1,0]
	v_pk_mul_f32 v[70:71], v[70:71], v[134:135] op_sel_hi:[1,0]
	v_pk_mul_f32 v[64:65], v[64:65], v[134:135] op_sel_hi:[1,0]
	v_pk_mul_f32 v[66:67], v[66:67], v[134:135] op_sel_hi:[1,0]
	v_pk_mul_f32 v[68:69], v[68:69], v[76:77]
	v_pk_mul_f32 v[70:71], v[70:71], v[78:79]
	v_pk_mul_f32 v[64:65], v[64:65], v[72:73]
	v_pk_mul_f32 v[66:67], v[66:67], v[74:75]
	v_add_u32_e32 v129, 0x42000, v128
	v_cvt_pk_bf16_f32 v76, v68, v69
	v_cvt_pk_bf16_f32 v77, v70, v71
	v_cvt_pk_bf16_f32 v78, v64, v65
	v_cvt_pk_bf16_f32 v79, v66, v67
	global_store_dwordx4 v129, v[76:79], s[28:29] sc1
	v_fmamk_f32 v132, v171, 0x3a800000, v162
	v_cmp_gt_f32_e32 vcc, s40, v132
	v_mul_f32_e32 v133, 0x4b800000, v132
	v_pk_mul_f32 v[52:53], v[60:61], v[52:53]
	v_pk_mul_f32 v[54:55], v[62:63], v[54:55]
	v_cndmask_b32_e32 v132, v132, v133, vcc
	v_rsq_f32_e32 v132, v132
	v_pk_mul_f32 v[48:49], v[56:57], v[48:49]
	v_pk_mul_f32 v[50:51], v[58:59], v[50:51]
	v_mul_f32_e32 v133, 0x45800000, v132
	v_cndmask_b32_e32 v132, v132, v133, vcc
	v_cndmask_b32_e64 v132, v132, 1.0, s[14:15]
	v_mul_f32_e32 v130, 0xbfb8aa3b, v132
	v_mul_f32_e32 v134, v132, v132
	v_pk_mul_f32 v[60:61], v[60:61], v[130:131] op_sel_hi:[1,0]
	v_pk_mul_f32 v[62:63], v[62:63], v[130:131] op_sel_hi:[1,0]
	v_pk_mul_f32 v[56:57], v[56:57], v[130:131] op_sel_hi:[1,0]
	v_pk_mul_f32 v[58:59], v[58:59], v[130:131] op_sel_hi:[1,0]
	v_exp_f32_e32 v60, v60
	v_exp_f32_e32 v61, v61
	v_exp_f32_e32 v62, v62
	v_exp_f32_e32 v63, v63
	v_exp_f32_e32 v56, v56
	v_exp_f32_e32 v57, v57
	v_exp_f32_e32 v58, v58
	v_exp_f32_e32 v59, v59
	v_pk_add_f32 v[60:61], v[60:61], v[160:161]
	v_pk_add_f32 v[62:63], v[62:63], v[160:161]
	v_pk_add_f32 v[56:57], v[56:57], v[160:161]
	v_pk_add_f32 v[58:59], v[58:59], v[160:161]
	v_rcp_f32_e32 v60, v60
	v_rcp_f32_e32 v61, v61
	v_rcp_f32_e32 v62, v62
	v_rcp_f32_e32 v63, v63
	v_rcp_f32_e32 v56, v56
	v_rcp_f32_e32 v57, v57
	v_rcp_f32_e32 v58, v58
	v_rcp_f32_e32 v59, v59
	v_pk_mul_f32 v[52:53], v[52:53], v[134:135] op_sel_hi:[1,0]
	v_pk_mul_f32 v[54:55], v[54:55], v[134:135] op_sel_hi:[1,0]
	v_pk_mul_f32 v[48:49], v[48:49], v[134:135] op_sel_hi:[1,0]
	v_pk_mul_f32 v[50:51], v[50:51], v[134:135] op_sel_hi:[1,0]
	v_pk_mul_f32 v[52:53], v[52:53], v[60:61]
	v_pk_mul_f32 v[54:55], v[54:55], v[62:63]
	v_pk_mul_f32 v[48:49], v[48:49], v[56:57]
	v_pk_mul_f32 v[50:51], v[50:51], v[58:59]
	v_add_u32_e32 v129, 0xb0000, v128
	v_cvt_pk_bf16_f32 v60, v52, v53
	v_cvt_pk_bf16_f32 v61, v54, v55
	v_cvt_pk_bf16_f32 v62, v48, v49
	v_cvt_pk_bf16_f32 v63, v50, v51
	global_store_dwordx4 v129, v[60:63], s[28:29] sc1
	v_fmamk_f32 v132, v172, 0x3a800000, v162
	v_cmp_gt_f32_e32 vcc, s40, v132
	v_mul_f32_e32 v133, 0x4b800000, v132
	v_pk_mul_f32 v[36:37], v[44:45], v[36:37]
	v_pk_mul_f32 v[38:39], v[46:47], v[38:39]
	v_cndmask_b32_e32 v132, v132, v133, vcc
	v_rsq_f32_e32 v132, v132
	v_pk_mul_f32 v[32:33], v[40:41], v[32:33]
	v_pk_mul_f32 v[34:35], v[42:43], v[34:35]
	v_mul_f32_e32 v133, 0x45800000, v132
	v_cndmask_b32_e32 v132, v132, v133, vcc
	v_cndmask_b32_e64 v132, v132, 1.0, s[14:15]
	v_mul_f32_e32 v130, 0xbfb8aa3b, v132
	v_mul_f32_e32 v134, v132, v132
	v_pk_mul_f32 v[44:45], v[44:45], v[130:131] op_sel_hi:[1,0]
	v_pk_mul_f32 v[46:47], v[46:47], v[130:131] op_sel_hi:[1,0]
	v_pk_mul_f32 v[40:41], v[40:41], v[130:131] op_sel_hi:[1,0]
	v_pk_mul_f32 v[42:43], v[42:43], v[130:131] op_sel_hi:[1,0]
	v_exp_f32_e32 v44, v44
	v_exp_f32_e32 v45, v45
	v_exp_f32_e32 v46, v46
	v_exp_f32_e32 v47, v47
	v_exp_f32_e32 v40, v40
	v_exp_f32_e32 v41, v41
	v_exp_f32_e32 v42, v42
	v_exp_f32_e32 v43, v43
	v_pk_add_f32 v[44:45], v[44:45], v[160:161]
	v_pk_add_f32 v[46:47], v[46:47], v[160:161]
	v_pk_add_f32 v[40:41], v[40:41], v[160:161]
	v_pk_add_f32 v[42:43], v[42:43], v[160:161]
	v_rcp_f32_e32 v44, v44
	v_rcp_f32_e32 v45, v45
	v_rcp_f32_e32 v46, v46
	v_rcp_f32_e32 v47, v47
	v_rcp_f32_e32 v40, v40
	v_rcp_f32_e32 v41, v41
	v_rcp_f32_e32 v42, v42
	v_rcp_f32_e32 v43, v43
	v_pk_mul_f32 v[36:37], v[36:37], v[134:135] op_sel_hi:[1,0]
	v_pk_mul_f32 v[38:39], v[38:39], v[134:135] op_sel_hi:[1,0]
	v_pk_mul_f32 v[32:33], v[32:33], v[134:135] op_sel_hi:[1,0]
	v_pk_mul_f32 v[34:35], v[34:35], v[134:135] op_sel_hi:[1,0]
	v_pk_mul_f32 v[36:37], v[36:37], v[44:45]
	v_pk_mul_f32 v[38:39], v[38:39], v[46:47]
	v_pk_mul_f32 v[32:33], v[32:33], v[40:41]
	v_pk_mul_f32 v[34:35], v[34:35], v[42:43]
	v_add_u32_e32 v129, 0xc6000, v128
	v_cvt_pk_bf16_f32 v44, v36, v37
	v_cvt_pk_bf16_f32 v45, v38, v39
	v_cvt_pk_bf16_f32 v46, v32, v33
	v_cvt_pk_bf16_f32 v47, v34, v35
	global_store_dwordx4 v129, v[44:47], s[28:29] sc1
	v_fmamk_f32 v132, v174, 0x3a800000, v162
	v_cmp_gt_f32_e32 vcc, s40, v132
	v_mul_f32_e32 v133, 0x4b800000, v132
	v_pk_mul_f32 v[20:21], v[28:29], v[20:21]
	v_pk_mul_f32 v[22:23], v[30:31], v[22:23]
	v_cndmask_b32_e32 v132, v132, v133, vcc
	v_rsq_f32_e32 v132, v132
	v_pk_mul_f32 v[16:17], v[24:25], v[16:17]
	v_pk_mul_f32 v[18:19], v[26:27], v[18:19]
	v_mul_f32_e32 v133, 0x45800000, v132
	v_cndmask_b32_e32 v132, v132, v133, vcc
	v_cndmask_b32_e64 v132, v132, 1.0, s[14:15]
	v_mul_f32_e32 v130, 0xbfb8aa3b, v132
	v_mul_f32_e32 v134, v132, v132
	v_pk_mul_f32 v[28:29], v[28:29], v[130:131] op_sel_hi:[1,0]
	v_pk_mul_f32 v[30:31], v[30:31], v[130:131] op_sel_hi:[1,0]
	v_pk_mul_f32 v[24:25], v[24:25], v[130:131] op_sel_hi:[1,0]
	v_pk_mul_f32 v[26:27], v[26:27], v[130:131] op_sel_hi:[1,0]
	v_exp_f32_e32 v28, v28
	v_exp_f32_e32 v29, v29
	v_exp_f32_e32 v30, v30
	v_exp_f32_e32 v31, v31
	v_exp_f32_e32 v24, v24
	v_exp_f32_e32 v25, v25
	v_exp_f32_e32 v26, v26
	v_exp_f32_e32 v27, v27
	v_pk_add_f32 v[28:29], v[28:29], v[160:161]
	v_pk_add_f32 v[30:31], v[30:31], v[160:161]
	v_pk_add_f32 v[24:25], v[24:25], v[160:161]
	v_pk_add_f32 v[26:27], v[26:27], v[160:161]
	v_rcp_f32_e32 v28, v28
	v_rcp_f32_e32 v29, v29
	v_rcp_f32_e32 v30, v30
	v_rcp_f32_e32 v31, v31
	v_rcp_f32_e32 v24, v24
	v_rcp_f32_e32 v25, v25
	v_rcp_f32_e32 v26, v26
	v_rcp_f32_e32 v27, v27
	v_pk_mul_f32 v[20:21], v[20:21], v[134:135] op_sel_hi:[1,0]
	v_pk_mul_f32 v[22:23], v[22:23], v[134:135] op_sel_hi:[1,0]
	v_pk_mul_f32 v[16:17], v[16:17], v[134:135] op_sel_hi:[1,0]
	v_pk_mul_f32 v[18:19], v[18:19], v[134:135] op_sel_hi:[1,0]
	v_pk_mul_f32 v[20:21], v[20:21], v[28:29]
	v_pk_mul_f32 v[22:23], v[22:23], v[30:31]
	v_pk_mul_f32 v[16:17], v[16:17], v[24:25]
	v_pk_mul_f32 v[18:19], v[18:19], v[26:27]
	v_add_u32_e32 v129, 0xdc000, v128
	v_cvt_pk_bf16_f32 v28, v20, v21
	v_cvt_pk_bf16_f32 v29, v22, v23
	v_cvt_pk_bf16_f32 v30, v16, v17
	v_cvt_pk_bf16_f32 v31, v18, v19
	global_store_dwordx4 v129, v[28:31], s[28:29] sc1
	v_fmamk_f32 v132, v173, 0x3a800000, v162
	v_cmp_gt_f32_e32 vcc, s40, v132
	v_mul_f32_e32 v133, 0x4b800000, v132
	v_pk_mul_f32 v[4:5], v[12:13], v[4:5]
	v_pk_mul_f32 v[6:7], v[14:15], v[6:7]
	v_cndmask_b32_e32 v132, v132, v133, vcc
	v_rsq_f32_e32 v132, v132
	v_pk_mul_f32 v[0:1], v[8:9], v[0:1]
	v_pk_mul_f32 v[2:3], v[10:11], v[2:3]
	v_mul_f32_e32 v133, 0x45800000, v132
	v_cndmask_b32_e32 v132, v132, v133, vcc
	v_cndmask_b32_e64 v132, v132, 1.0, s[14:15]
	v_mul_f32_e32 v130, 0xbfb8aa3b, v132
	v_mul_f32_e32 v134, v132, v132
	v_pk_mul_f32 v[12:13], v[12:13], v[130:131] op_sel_hi:[1,0]
	v_pk_mul_f32 v[14:15], v[14:15], v[130:131] op_sel_hi:[1,0]
	v_pk_mul_f32 v[8:9], v[8:9], v[130:131] op_sel_hi:[1,0]
	v_pk_mul_f32 v[10:11], v[10:11], v[130:131] op_sel_hi:[1,0]
	v_exp_f32_e32 v12, v12
	v_exp_f32_e32 v13, v13
	v_exp_f32_e32 v14, v14
	v_exp_f32_e32 v15, v15
	v_exp_f32_e32 v8, v8
	v_exp_f32_e32 v9, v9
	v_exp_f32_e32 v10, v10
	v_exp_f32_e32 v11, v11
	v_pk_add_f32 v[12:13], v[12:13], v[160:161]
	v_pk_add_f32 v[14:15], v[14:15], v[160:161]
	v_pk_add_f32 v[8:9], v[8:9], v[160:161]
	v_pk_add_f32 v[10:11], v[10:11], v[160:161]
	v_rcp_f32_e32 v12, v12
	v_rcp_f32_e32 v13, v13
	v_rcp_f32_e32 v14, v14
	v_rcp_f32_e32 v15, v15
	v_rcp_f32_e32 v8, v8
	v_rcp_f32_e32 v9, v9
	v_rcp_f32_e32 v10, v10
	v_rcp_f32_e32 v11, v11
	v_pk_mul_f32 v[4:5], v[4:5], v[134:135] op_sel_hi:[1,0]
	v_pk_mul_f32 v[6:7], v[6:7], v[134:135] op_sel_hi:[1,0]
	v_pk_mul_f32 v[0:1], v[0:1], v[134:135] op_sel_hi:[1,0]
	v_pk_mul_f32 v[2:3], v[2:3], v[134:135] op_sel_hi:[1,0]
	v_pk_mul_f32 v[4:5], v[4:5], v[12:13]
	v_pk_mul_f32 v[6:7], v[6:7], v[14:15]
	v_pk_mul_f32 v[0:1], v[0:1], v[8:9]
	v_pk_mul_f32 v[2:3], v[2:3], v[10:11]
	v_add_u32_e32 v129, 0xf2000, v128
	v_cvt_pk_bf16_f32 v12, v4, v5
	v_cvt_pk_bf16_f32 v13, v6, v7
	v_cvt_pk_bf16_f32 v14, v0, v1
	v_cvt_pk_bf16_f32 v15, v2, v3
	global_store_dwordx4 v129, v[12:15], s[28:29] sc1
	s_and_b64 vcc, exec, s[38:39]
	s_cbranch_vccz .LBB0_158

.Lfz_bar:
	v_readlane_b32 s0, v240, 23
	s_cmp_eq_u32 s0, 0
	s_cbranch_scc1 .Llz_arrive
	s_cmp_eq_u32 s0, 7
	s_cbranch_scc0 .Llz_normal
.Llz_arrive:
	s_waitcnt vmcnt(0) lgkmcnt(0)
	s_barrier
	v_readlane_b32 s2, v244, 9
	s_add_i32 s2, s2, 0x100
	v_writelane_b32 v244, s2, 9
	s_mov_b32 s2, 1
	v_writelane_b32 v244, s2, 8
	v_cmp_eq_u32_e32 vcc, 0, v147
	s_and_saveexec_b64 s[0:1], vcc
	s_cbranch_execz .Llz_arrived
	v_readlane_b32 s2, v241, 24
	v_readlane_b32 s3, v241, 25
	s_add_u32 s2, s2, 0x1000
	s_addc_u32 s3, s3, 0
	s_nop 4
	global_atomic_add v137, v163, s[2:3]

	.amdhsa_kernel _Z4mega6Params
		.amdhsa_group_segment_fixed_size 0
		.amdhsa_private_segment_fixed_size 0
		.amdhsa_kernarg_size 512
		.amdhsa_user_sgpr_count 2
		.amdhsa_user_sgpr_dispatch_ptr 0
		.amdhsa_user_sgpr_queue_ptr 0
		.amdhsa_user_sgpr_kernarg_segment_ptr 1
		.amdhsa_user_sgpr_dispatch_id 0
		.amdhsa_user_sgpr_kernarg_preload_length 0
		.amdhsa_user_sgpr_kernarg_preload_offset 0
		.amdhsa_user_sgpr_private_segment_size 0
		.amdhsa_uses_dynamic_stack 0
		.amdhsa_enable_private_segment 0
		.amdhsa_system_sgpr_workgroup_id_x 1
		.amdhsa_system_sgpr_workgroup_id_y 0
		.amdhsa_system_sgpr_workgroup_id_z 0
		.amdhsa_system_sgpr_workgroup_info 0
		.amdhsa_system_vgpr_workitem_id 2
		.amdhsa_next_free_vgpr 256
		.amdhsa_next_free_sgpr 100
		.amdhsa_accum_offset 256
		.amdhsa_reserve_vcc 1
		.amdhsa_float_round_mode_32 0
		.amdhsa_float_round_mode_16_64 0
		.amdhsa_float_denorm_mode_32 3
		.amdhsa_float_denorm_mode_16_64 3
		.amdhsa_dx10_clamp 1
		.amdhsa_ieee_mode 1
		.amdhsa_fp16_overflow 0
		.amdhsa_tg_split 0
		.amdhsa_exception_fp_ieee_invalid_op 0
		.amdhsa_exception_fp_denorm_src 0
		.amdhsa_exception_fp_ieee_div_zero 0
		.amdhsa_exception_fp_ieee_overflow 0
		.amdhsa_exception_fp_ieee_underflow 0
		.amdhsa_exception_fp_ieee_inexact 0
		.amdhsa_exception_int_div_zero 0
	.end_amdhsa_kernel

.Lfunc_end0:
	.size	_Z4mega6Params, .Lfunc_end0-_Z4mega6Params
	.set _Z4mega6Params.num_vgpr, 256
	.set _Z4mega6Params.num_agpr, 0
	.set _Z4mega6Params.numbered_sgpr, 100
	.set _Z4mega6Params.num_named_barrier, 0
	.set _Z4mega6Params.private_seg_size, 0
	.set _Z4mega6Params.uses_vcc, 1
	.set _Z4mega6Params.uses_flat_scratch, 0
	.set _Z4mega6Params.has_dyn_sized_stack, 0
	.set _Z4mega6Params.has_recursion, 0
	.set _Z4mega6Params.has_indirect_call, 0

amdhsa.kernels:
  - .agpr_count:     0
    .args:
      - .offset:         0
        .size:           256
        .value_kind:     by_value
      - .offset:         256
        .size:           4
        .value_kind:     hidden_block_count_x
      - .offset:         260
        .size:           4
        .value_kind:     hidden_block_count_y
      - .offset:         264
        .size:           4
        .value_kind:     hidden_block_count_z
      - .offset:         268
        .size:           2
        .value_kind:     hidden_group_size_x
      - .offset:         270
        .size:           2
        .value_kind:     hidden_group_size_y
      - .offset:         272
        .size:           2
        .value_kind:     hidden_group_size_z
      - .offset:         274
        .size:           2
        .value_kind:     hidden_remainder_x
      - .offset:         276
        .size:           2
        .value_kind:     hidden_remainder_y
      - .offset:         278
        .size:           2
        .value_kind:     hidden_remainder_z
      - .offset:         296
        .size:           8
        .value_kind:     hidden_global_offset_x
      - .offset:         304
        .size:           8
        .value_kind:     hidden_global_offset_y
      - .offset:         312
        .size:           8
        .value_kind:     hidden_global_offset_z
      - .offset:         320
        .size:           2
        .value_kind:     hidden_grid_dims
      - .offset:         344
        .size:           8
        .value_kind:     hidden_multigrid_sync_arg
      - .offset:         376
        .size:           4
        .value_kind:     hidden_dynamic_lds_size
    .group_segment_fixed_size: 0
    .kernarg_segment_align: 8
    .kernarg_segment_size: 512
    .language:       OpenCL C
    .language_version:
      - 2
      - 0
    .max_flat_workgroup_size: 512
    .name:           _Z4mega6Params
    .private_segment_fixed_size: 0
    .sgpr_count:     106
    .sgpr_spill_count: 274
    .symbol:         _Z4mega6Params.kd
    .uniform_work_group_size: 1
    .uses_dynamic_stack: false
    .vgpr_count:     256
    .vgpr_spill_count: 0
    .wavefront_size: 64
